# XCD barrier: release is the top-level arrival counter reaching its episode target; waiters poll it, no separate generation bump by the last leader
# speedup vs baseline: 1.0039x; 1.0039x over previous
.LBB0_96:
	s_or_b64 exec, exec, s[8:9]
	v_cvt_f32_u32_e32 v4, v2
	s_waitcnt vmcnt(0)
	v_readfirstlane_b32 s1, v3
	v_sub_u32_e32 v3, 0, v2
	v_rcp_iflag_f32_e32 v4, v4
	v_add_u32_e32 v5, s1, v1
	v_mul_f32_e32 v4, 0x4f7ffffe, v4
	v_cvt_u32_f32_e32 v4, v4
	v_mul_lo_u32 v1, v3, v4
	v_mul_hi_u32 v1, v4, v1
	v_add_u32_e32 v1, v4, v1
	v_mul_hi_u32 v1, v5, v1
	v_mul_lo_u32 v3, v1, v2
	v_sub_u32_e32 v3, v5, v3
	v_add_u32_e32 v4, 1, v1
	v_cmp_ge_u32_e32 vcc, v3, v2
	s_nop 1
	v_cndmask_b32_e32 v1, v1, v4, vcc
	v_sub_u32_e32 v4, v3, v2
	v_cndmask_b32_e32 v3, v3, v4, vcc
	v_add_u32_e32 v4, 1, v1
	v_cmp_ge_u32_e32 vcc, v3, v2
	v_add_u32_e32 v3, 1, v5
	s_nop 0
	v_cndmask_b32_e32 v1, v1, v4, vcc
	v_mul_lo_u32 v4, v2, v1
	v_add_u32_e32 v2, v4, v2
	v_cmp_ne_u32_e32 vcc, v3, v2
	s_and_saveexec_b64 s[6:7], vcc
	s_xor_b64 s[6:7], exec, s[6:7]
	s_cbranch_execz .LBB0_110
	s_waitcnt lgkmcnt(0)
	v_readlane_b32 s98, v254, 38
	s_nop 3
	s_lshl_b32 s98, s98, 8
	s_sub_u32 s98, s4, s98
	s_subb_u32 s99, s5, 0
	s_add_u32 s14, s98, 0x3400
	s_addc_u32 s15, s99, 0
	v_mad_u32_u24 v1, v1, v0, v0
	v_mov_b32_e32 v0, 0
	global_load_dword v0, v0, s[14:15] sc1
	s_waitcnt vmcnt(0)
	v_cmp_lt_u32_e32 vcc, v0, v1
	s_and_saveexec_b64 s[8:9], vcc
	s_cbranch_execz .LBB0_109
	s_add_u32 s10, s78, 0x80200
	s_addc_u32 s11, s79, 0
	s_mov_b32 s1, 1
	s_mov_b64 s[16:17], 0
	v_mov_b32_e32 v0, 0
	s_branch .LBB0_100

.LBB0_104:
	global_load_dword v2, v0, s[14:15] sc1
	s_add_i32 s1, s1, 1
	s_mov_b64 s[22:23], -1
	s_waitcnt vmcnt(0)
	v_cmp_ge_u32_e32 vcc, v2, v1
	s_orn2_b64 s[20:21], vcc, exec
	s_branch .LBB0_99

.LBB0_113:
	s_or_b64 exec, exec, s[8:9]
	v_cvt_f32_u32_e32 v3, v0
	s_waitcnt vmcnt(0)
	v_readfirstlane_b32 s1, v2
	s_add_u32 s8, s78, 0x83400
	s_addc_u32 s9, s79, 0
	v_rcp_iflag_f32_e32 v3, v3
	v_add_u32_e32 v1, s1, v1
	v_add_u32_e32 v4, 1, v1
	s_mov_b64 s[10:11], 0
	v_mul_f32_e32 v2, 0x4f7ffffe, v3
	v_cvt_u32_f32_e32 v2, v2
	v_sub_u32_e32 v3, 0, v0
	v_mul_lo_u32 v3, v3, v2
	v_mul_hi_u32 v3, v2, v3
	v_add_u32_e32 v2, v2, v3
	v_mul_hi_u32 v2, v1, v2
	v_mul_lo_u32 v3, v2, v0
	v_sub_u32_e32 v1, v1, v3
	v_add_u32_e32 v5, 1, v2
	v_cmp_ge_u32_e32 vcc, v1, v0
	v_sub_u32_e32 v3, v1, v0
	s_nop 0
	v_cndmask_b32_e32 v2, v2, v5, vcc
	v_cndmask_b32_e32 v1, v1, v3, vcc
	v_add_u32_e32 v3, 1, v2
	v_cmp_ge_u32_e32 vcc, v1, v0
	s_nop 1
	v_cndmask_b32_e32 v2, v2, v3, vcc
	v_mul_lo_u32 v1, v0, v2
	v_add_u32_e32 v0, v1, v0
	v_mov_b32_e32 v5, v0
	v_cmp_ne_u32_e32 vcc, v4, v0
	v_mov_b64_e32 v[0:1], s[8:9]
	s_and_saveexec_b64 s[6:7], vcc
	s_cbranch_execz .LBB0_125
	v_mov_b32_e32 v0, 0
	global_load_dword v1, v0, s[8:9] sc1
	s_mov_b64 s[16:17], 0
	s_waitcnt vmcnt(0)
	v_cmp_lt_u32_e32 vcc, v1, v5
	s_and_saveexec_b64 s[14:15], vcc
	s_cbranch_execz .LBB0_124
	s_add_u32 s10, s78, 0x80200
	s_addc_u32 s11, s79, 0
	s_mov_b32 s1, 1
	s_branch .LBB0_117

.LBB0_121:
	global_load_dword v1, v0, s[8:9] sc1
	s_add_i32 s1, s1, 1
	s_mov_b64 s[20:21], -1
	s_waitcnt vmcnt(0)
	v_cmp_ge_u32_e32 vcc, v1, v5
	s_orn2_b64 s[24:25], vcc, exec
	s_branch .LBB0_116

.LBB0_217:
	s_or_b64 exec, exec, s[8:9]
	v_cvt_f32_u32_e32 v4, v2
	s_waitcnt vmcnt(0)
	v_readfirstlane_b32 s1, v3
	v_sub_u32_e32 v3, 0, v2
	v_rcp_iflag_f32_e32 v4, v4
	v_add_u32_e32 v5, s1, v1
	v_mul_f32_e32 v4, 0x4f7ffffe, v4
	v_cvt_u32_f32_e32 v4, v4
	v_mul_lo_u32 v1, v3, v4
	v_mul_hi_u32 v1, v4, v1
	v_add_u32_e32 v1, v4, v1
	v_mul_hi_u32 v1, v5, v1
	v_mul_lo_u32 v3, v1, v2
	v_sub_u32_e32 v3, v5, v3
	v_add_u32_e32 v4, 1, v1
	v_cmp_ge_u32_e32 vcc, v3, v2
	s_nop 1
	v_cndmask_b32_e32 v1, v1, v4, vcc
	v_sub_u32_e32 v4, v3, v2
	v_cndmask_b32_e32 v3, v3, v4, vcc
	v_add_u32_e32 v4, 1, v1
	v_cmp_ge_u32_e32 vcc, v3, v2
	v_add_u32_e32 v3, 1, v5
	s_nop 0
	v_cndmask_b32_e32 v1, v1, v4, vcc
	v_mul_lo_u32 v4, v2, v1
	v_add_u32_e32 v2, v4, v2
	v_cmp_ne_u32_e32 vcc, v3, v2
	s_and_saveexec_b64 s[6:7], vcc
	s_xor_b64 s[6:7], exec, s[6:7]
	s_cbranch_execz .LBB0_231
	s_waitcnt lgkmcnt(0)
	v_readlane_b32 s98, v254, 38
	s_nop 3
	s_lshl_b32 s98, s98, 8
	s_sub_u32 s98, s4, s98
	s_subb_u32 s99, s5, 0
	s_add_u32 s16, s98, 0x3400
	s_addc_u32 s17, s99, 0
	v_mad_u32_u24 v1, v1, v0, v0
	v_mov_b32_e32 v0, 0
	global_load_dword v0, v0, s[16:17] sc1
	s_waitcnt vmcnt(0)
	v_cmp_lt_u32_e32 vcc, v0, v1
	s_and_saveexec_b64 s[8:9], vcc
	s_cbranch_execz .LBB0_230
	s_add_u32 s10, s78, 0x80200
	s_addc_u32 s11, s79, 0
	s_mov_b32 s1, 1
	s_mov_b64 s[18:19], 0
	v_mov_b32_e32 v0, 0
	s_branch .LBB0_221

.LBB0_225:
	global_load_dword v2, v0, s[16:17] sc1
	s_add_i32 s1, s1, 1
	s_mov_b64 s[24:25], -1
	s_waitcnt vmcnt(0)
	v_cmp_ge_u32_e32 vcc, v2, v1
	s_orn2_b64 s[22:23], vcc, exec
	s_branch .LBB0_220

.LBB0_234:
	s_or_b64 exec, exec, s[8:9]
	v_cvt_f32_u32_e32 v3, v0
	s_waitcnt vmcnt(0)
	v_readfirstlane_b32 s1, v2
	s_add_u32 s8, s78, 0x83400
	s_addc_u32 s9, s79, 0
	v_rcp_iflag_f32_e32 v3, v3
	v_add_u32_e32 v1, s1, v1
	v_add_u32_e32 v4, 1, v1
	s_mov_b64 s[10:11], 0
	v_mul_f32_e32 v2, 0x4f7ffffe, v3
	v_cvt_u32_f32_e32 v2, v2
	v_sub_u32_e32 v3, 0, v0
	v_mul_lo_u32 v3, v3, v2
	v_mul_hi_u32 v3, v2, v3
	v_add_u32_e32 v2, v2, v3
	v_mul_hi_u32 v2, v1, v2
	v_mul_lo_u32 v3, v2, v0
	v_sub_u32_e32 v1, v1, v3
	v_add_u32_e32 v5, 1, v2
	v_cmp_ge_u32_e32 vcc, v1, v0
	v_sub_u32_e32 v3, v1, v0
	s_nop 0
	v_cndmask_b32_e32 v2, v2, v5, vcc
	v_cndmask_b32_e32 v1, v1, v3, vcc
	v_add_u32_e32 v3, 1, v2
	v_cmp_ge_u32_e32 vcc, v1, v0
	s_nop 1
	v_cndmask_b32_e32 v2, v2, v3, vcc
	v_mul_lo_u32 v1, v0, v2
	v_add_u32_e32 v0, v1, v0
	v_mov_b32_e32 v5, v0
	v_cmp_ne_u32_e32 vcc, v4, v0
	v_mov_b64_e32 v[0:1], s[8:9]
	s_and_saveexec_b64 s[6:7], vcc
	s_cbranch_execz .LBB0_246
	v_mov_b32_e32 v0, 0
	global_load_dword v1, v0, s[8:9] sc1
	s_mov_b64 s[18:19], 0
	s_waitcnt vmcnt(0)
	v_cmp_lt_u32_e32 vcc, v1, v5
	s_and_saveexec_b64 s[16:17], vcc
	s_cbranch_execz .LBB0_245
	s_add_u32 s10, s78, 0x80200
	s_addc_u32 s11, s79, 0
	s_mov_b32 s1, 1
	s_branch .LBB0_238

.LBB0_242:
	global_load_dword v1, v0, s[8:9] sc1
	s_add_i32 s1, s1, 1
	s_mov_b64 s[22:23], -1
	s_waitcnt vmcnt(0)
	v_cmp_ge_u32_e32 vcc, v1, v5
	s_orn2_b64 s[26:27], vcc, exec
	s_branch .LBB0_237

.LBB0_759:
	s_or_b64 exec, exec, s[6:7]
	v_cvt_f32_u32_e32 v4, v2
	s_waitcnt vmcnt(0)
	v_readfirstlane_b32 s4, v3
	v_sub_u32_e32 v3, 0, v2
	v_rcp_iflag_f32_e32 v4, v4
	v_add_u32_e32 v5, s4, v1
	v_mul_f32_e32 v4, 0x4f7ffffe, v4
	v_cvt_u32_f32_e32 v4, v4
	v_mul_lo_u32 v1, v3, v4
	v_mul_hi_u32 v1, v4, v1
	v_add_u32_e32 v1, v4, v1
	v_mul_hi_u32 v1, v5, v1
	v_mul_lo_u32 v3, v1, v2
	v_sub_u32_e32 v3, v5, v3
	v_add_u32_e32 v4, 1, v1
	v_cmp_ge_u32_e32 vcc, v3, v2
	s_nop 1
	v_cndmask_b32_e32 v1, v1, v4, vcc
	v_sub_u32_e32 v4, v3, v2
	v_cndmask_b32_e32 v3, v3, v4, vcc
	v_add_u32_e32 v4, 1, v1
	v_cmp_ge_u32_e32 vcc, v3, v2
	v_add_u32_e32 v3, 1, v5
	s_nop 0
	v_cndmask_b32_e32 v1, v1, v4, vcc
	v_mul_lo_u32 v4, v2, v1
	v_add_u32_e32 v2, v4, v2
	v_cmp_ne_u32_e32 vcc, v3, v2
	s_and_saveexec_b64 s[4:5], vcc
	s_xor_b64 s[4:5], exec, s[4:5]
	s_cbranch_execz .LBB0_773
	s_waitcnt lgkmcnt(0)
	v_readlane_b32 s98, v254, 38
	s_nop 3
	s_lshl_b32 s98, s98, 8
	s_sub_u32 s98, s2, s98
	s_subb_u32 s99, s3, 0
	s_add_u32 s10, s98, 0x3400
	s_addc_u32 s11, s99, 0
	v_mad_u32_u24 v1, v1, v0, v0
	v_mov_b32_e32 v0, 0
	global_load_dword v0, v0, s[10:11] sc1
	s_waitcnt vmcnt(0)
	v_cmp_lt_u32_e32 vcc, v0, v1
	s_and_saveexec_b64 s[6:7], vcc
	s_cbranch_execz .LBB0_772
	s_add_u32 s8, s78, 0x80200
	s_addc_u32 s9, s79, 0
	s_mov_b32 s22, 1
	s_mov_b64 s[12:13], 0
	v_mov_b32_e32 v0, 0
	s_branch .LBB0_763

.LBB0_767:
	global_load_dword v2, v0, s[10:11] sc1
	s_add_i32 s22, s22, 1
	s_mov_b64 s[18:19], -1
	s_waitcnt vmcnt(0)
	v_cmp_ge_u32_e32 vcc, v2, v1
	s_orn2_b64 s[16:17], vcc, exec
	s_branch .LBB0_762

.LBB0_776:
	s_or_b64 exec, exec, s[6:7]
	v_cvt_f32_u32_e32 v3, v0
	s_waitcnt vmcnt(0)
	v_readfirstlane_b32 s4, v2
	s_add_u32 s6, s78, 0x83400
	s_addc_u32 s7, s79, 0
	v_rcp_iflag_f32_e32 v3, v3
	v_add_u32_e32 v1, s4, v1
	v_add_u32_e32 v4, 1, v1
	s_mov_b64 s[8:9], 0
	v_mul_f32_e32 v2, 0x4f7ffffe, v3
	v_cvt_u32_f32_e32 v2, v2
	v_sub_u32_e32 v3, 0, v0
	v_mul_lo_u32 v3, v3, v2
	v_mul_hi_u32 v3, v2, v3
	v_add_u32_e32 v2, v2, v3
	v_mul_hi_u32 v2, v1, v2
	v_mul_lo_u32 v3, v2, v0
	v_sub_u32_e32 v1, v1, v3
	v_add_u32_e32 v5, 1, v2
	v_cmp_ge_u32_e32 vcc, v1, v0
	v_sub_u32_e32 v3, v1, v0
	s_nop 0
	v_cndmask_b32_e32 v2, v2, v5, vcc
	v_cndmask_b32_e32 v1, v1, v3, vcc
	v_add_u32_e32 v3, 1, v2
	v_cmp_ge_u32_e32 vcc, v1, v0
	s_nop 1
	v_cndmask_b32_e32 v2, v2, v3, vcc
	v_mul_lo_u32 v1, v0, v2
	v_add_u32_e32 v0, v1, v0
	v_mov_b32_e32 v5, v0
	v_cmp_ne_u32_e32 vcc, v4, v0
	v_mov_b64_e32 v[0:1], s[6:7]
	s_and_saveexec_b64 s[4:5], vcc
	s_cbranch_execz .LBB0_788
	v_mov_b32_e32 v0, 0
	global_load_dword v1, v0, s[6:7] sc1
	s_mov_b64 s[12:13], 0
	s_waitcnt vmcnt(0)
	v_cmp_lt_u32_e32 vcc, v1, v5
	s_and_saveexec_b64 s[10:11], vcc
	s_cbranch_execz .LBB0_787
	s_add_u32 s8, s78, 0x80200
	s_addc_u32 s9, s79, 0
	s_mov_b32 s22, 1
	s_branch .LBB0_780

.LBB0_784:
	global_load_dword v1, v0, s[6:7] sc1
	s_add_i32 s22, s22, 1
	s_mov_b64 s[16:17], -1
	s_waitcnt vmcnt(0)
	v_cmp_ge_u32_e32 vcc, v1, v5
	s_orn2_b64 s[20:21], vcc, exec
	s_branch .LBB0_779

.LBB0_1020:
	s_or_b64 exec, exec, s[8:9]
	v_cvt_f32_u32_e32 v4, v2
	s_waitcnt vmcnt(0)
	v_readfirstlane_b32 s6, v3
	v_sub_u32_e32 v3, 0, v2
	v_rcp_iflag_f32_e32 v4, v4
	v_add_u32_e32 v5, s6, v1
	v_mul_f32_e32 v4, 0x4f7ffffe, v4
	v_cvt_u32_f32_e32 v4, v4
	v_mul_lo_u32 v1, v3, v4
	v_mul_hi_u32 v1, v4, v1
	v_add_u32_e32 v1, v4, v1
	v_mul_hi_u32 v1, v5, v1
	v_mul_lo_u32 v3, v1, v2
	v_sub_u32_e32 v3, v5, v3
	v_add_u32_e32 v4, 1, v1
	v_cmp_ge_u32_e32 vcc, v3, v2
	s_nop 1
	v_cndmask_b32_e32 v1, v1, v4, vcc
	v_sub_u32_e32 v4, v3, v2
	v_cndmask_b32_e32 v3, v3, v4, vcc
	v_add_u32_e32 v4, 1, v1
	v_cmp_ge_u32_e32 vcc, v3, v2
	v_add_u32_e32 v3, 1, v5
	s_nop 0
	v_cndmask_b32_e32 v1, v1, v4, vcc
	v_mul_lo_u32 v4, v2, v1
	v_add_u32_e32 v2, v4, v2
	v_cmp_ne_u32_e32 vcc, v3, v2
	s_and_saveexec_b64 s[6:7], vcc
	s_xor_b64 s[6:7], exec, s[6:7]
	s_cbranch_execz .LBB0_1034
	s_waitcnt lgkmcnt(0)
	v_readlane_b32 s98, v254, 38
	s_nop 3
	s_lshl_b32 s98, s98, 8
	s_sub_u32 s98, s4, s98
	s_subb_u32 s99, s5, 0
	s_add_u32 s12, s98, 0x3400
	s_addc_u32 s13, s99, 0
	v_mad_u32_u24 v1, v1, v0, v0
	v_mov_b32_e32 v0, 0
	global_load_dword v0, v0, s[12:13] sc1
	s_waitcnt vmcnt(0)
	v_cmp_lt_u32_e32 vcc, v0, v1
	s_and_saveexec_b64 s[8:9], vcc
	s_cbranch_execz .LBB0_1033
	s_add_u32 s10, s78, 0x80200
	s_addc_u32 s11, s79, 0
	s_mov_b32 s24, 1
	s_mov_b64 s[14:15], 0
	v_mov_b32_e32 v0, 0
	s_branch .LBB0_1024

.LBB0_1028:
	global_load_dword v2, v0, s[12:13] sc1
	s_add_i32 s24, s24, 1
	s_mov_b64 s[20:21], -1
	s_waitcnt vmcnt(0)
	v_cmp_ge_u32_e32 vcc, v2, v1
	s_orn2_b64 s[18:19], vcc, exec
	s_branch .LBB0_1023

.LBB0_1037:
	s_or_b64 exec, exec, s[8:9]
	v_cvt_f32_u32_e32 v3, v0
	s_waitcnt vmcnt(0)
	v_readfirstlane_b32 s6, v2
	s_add_u32 s8, s78, 0x83400
	s_addc_u32 s9, s79, 0
	v_rcp_iflag_f32_e32 v3, v3
	v_add_u32_e32 v1, s6, v1
	v_add_u32_e32 v4, 1, v1
	s_mov_b64 s[10:11], 0
	v_mul_f32_e32 v2, 0x4f7ffffe, v3
	v_cvt_u32_f32_e32 v2, v2
	v_sub_u32_e32 v3, 0, v0
	v_mul_lo_u32 v3, v3, v2
	v_mul_hi_u32 v3, v2, v3
	v_add_u32_e32 v2, v2, v3
	v_mul_hi_u32 v2, v1, v2
	v_mul_lo_u32 v3, v2, v0
	v_sub_u32_e32 v1, v1, v3
	v_add_u32_e32 v5, 1, v2
	v_cmp_ge_u32_e32 vcc, v1, v0
	v_sub_u32_e32 v3, v1, v0
	s_nop 0
	v_cndmask_b32_e32 v2, v2, v5, vcc
	v_cndmask_b32_e32 v1, v1, v3, vcc
	v_add_u32_e32 v3, 1, v2
	v_cmp_ge_u32_e32 vcc, v1, v0
	s_nop 1
	v_cndmask_b32_e32 v2, v2, v3, vcc
	v_mul_lo_u32 v1, v0, v2
	v_add_u32_e32 v0, v1, v0
	v_mov_b32_e32 v5, v0
	v_cmp_ne_u32_e32 vcc, v4, v0
	v_mov_b64_e32 v[0:1], s[8:9]
	s_and_saveexec_b64 s[6:7], vcc
	s_cbranch_execz .LBB0_1049
	v_mov_b32_e32 v0, 0
	global_load_dword v1, v0, s[8:9] sc1
	s_mov_b64 s[14:15], 0
	s_waitcnt vmcnt(0)
	v_cmp_lt_u32_e32 vcc, v1, v5
	s_and_saveexec_b64 s[12:13], vcc
	s_cbranch_execz .LBB0_1048
	s_add_u32 s10, s78, 0x80200
	s_addc_u32 s11, s79, 0
	s_mov_b32 s24, 1
	s_branch .LBB0_1041

.LBB0_1045:
	global_load_dword v1, v0, s[8:9] sc1
	s_add_i32 s24, s24, 1
	s_mov_b64 s[18:19], -1
	s_waitcnt vmcnt(0)
	v_cmp_ge_u32_e32 vcc, v1, v5
	s_orn2_b64 s[22:23], vcc, exec
	s_branch .LBB0_1040

.LBB0_1114:
	s_or_b64 exec, exec, s[6:7]
	v_cvt_f32_u32_e32 v4, v2
	s_waitcnt vmcnt(0)
	v_readfirstlane_b32 s4, v3
	v_sub_u32_e32 v3, 0, v2
	v_rcp_iflag_f32_e32 v4, v4
	v_add_u32_e32 v5, s4, v1
	v_mul_f32_e32 v4, 0x4f7ffffe, v4
	v_cvt_u32_f32_e32 v4, v4
	v_mul_lo_u32 v1, v3, v4
	v_mul_hi_u32 v1, v4, v1
	v_add_u32_e32 v1, v4, v1
	v_mul_hi_u32 v1, v5, v1
	v_mul_lo_u32 v3, v1, v2
	v_sub_u32_e32 v3, v5, v3
	v_add_u32_e32 v4, 1, v1
	v_cmp_ge_u32_e32 vcc, v3, v2
	s_nop 1
	v_cndmask_b32_e32 v1, v1, v4, vcc
	v_sub_u32_e32 v4, v3, v2
	v_cndmask_b32_e32 v3, v3, v4, vcc
	v_add_u32_e32 v4, 1, v1
	v_cmp_ge_u32_e32 vcc, v3, v2
	v_add_u32_e32 v3, 1, v5
	s_nop 0
	v_cndmask_b32_e32 v1, v1, v4, vcc
	v_mul_lo_u32 v4, v2, v1
	v_add_u32_e32 v2, v4, v2
	v_cmp_ne_u32_e32 vcc, v3, v2
	s_and_saveexec_b64 s[4:5], vcc
	s_xor_b64 s[4:5], exec, s[4:5]
	s_cbranch_execz .LBB0_1128
	s_waitcnt lgkmcnt(0)
	v_readlane_b32 s98, v254, 38
	s_nop 3
	s_lshl_b32 s98, s98, 8
	s_sub_u32 s98, s2, s98
	s_subb_u32 s99, s3, 0
	s_add_u32 s10, s98, 0x3400
	s_addc_u32 s11, s99, 0
	v_mad_u32_u24 v1, v1, v0, v0
	v_mov_b32_e32 v0, 0
	global_load_dword v0, v0, s[10:11] sc1
	s_waitcnt vmcnt(0)
	v_cmp_lt_u32_e32 vcc, v0, v1
	s_and_saveexec_b64 s[6:7], vcc
	s_cbranch_execz .LBB0_1127
	s_add_u32 s8, s78, 0x80200
	s_addc_u32 s9, s79, 0
	s_mov_b32 s24, 1
	s_mov_b64 s[14:15], 0
	v_mov_b32_e32 v0, 0
	s_branch .LBB0_1118

.LBB0_1122:
	global_load_dword v2, v0, s[10:11] sc1
	s_add_i32 s24, s24, 1
	s_mov_b64 s[20:21], -1
	s_waitcnt vmcnt(0)
	v_cmp_ge_u32_e32 vcc, v2, v1
	s_orn2_b64 s[18:19], vcc, exec
	s_branch .LBB0_1117

.LBB0_1131:
	s_or_b64 exec, exec, s[6:7]
	v_cvt_f32_u32_e32 v3, v0
	s_waitcnt vmcnt(0)
	v_readfirstlane_b32 s4, v2
	s_add_u32 s6, s78, 0x83400
	s_addc_u32 s7, s79, 0
	v_rcp_iflag_f32_e32 v3, v3
	v_add_u32_e32 v1, s4, v1
	v_add_u32_e32 v4, 1, v1
	s_mov_b64 s[8:9], 0
	v_mul_f32_e32 v2, 0x4f7ffffe, v3
	v_cvt_u32_f32_e32 v2, v2
	v_sub_u32_e32 v3, 0, v0
	v_mul_lo_u32 v3, v3, v2
	v_mul_hi_u32 v3, v2, v3
	v_add_u32_e32 v2, v2, v3
	v_mul_hi_u32 v2, v1, v2
	v_mul_lo_u32 v3, v2, v0
	v_sub_u32_e32 v1, v1, v3
	v_add_u32_e32 v5, 1, v2
	v_cmp_ge_u32_e32 vcc, v1, v0
	v_sub_u32_e32 v3, v1, v0
	s_nop 0
	v_cndmask_b32_e32 v2, v2, v5, vcc
	v_cndmask_b32_e32 v1, v1, v3, vcc
	v_add_u32_e32 v3, 1, v2
	v_cmp_ge_u32_e32 vcc, v1, v0
	s_nop 1
	v_cndmask_b32_e32 v2, v2, v3, vcc
	v_mul_lo_u32 v1, v0, v2
	v_add_u32_e32 v0, v1, v0
	v_mov_b32_e32 v5, v0
	v_cmp_ne_u32_e32 vcc, v4, v0
	v_mov_b64_e32 v[0:1], s[6:7]
	s_and_saveexec_b64 s[4:5], vcc
	s_cbranch_execz .LBB0_1143
	v_mov_b32_e32 v0, 0
	global_load_dword v1, v0, s[6:7] sc1
	s_mov_b64 s[14:15], 0
	s_waitcnt vmcnt(0)
	v_cmp_lt_u32_e32 vcc, v1, v5
	s_and_saveexec_b64 s[10:11], vcc
	s_cbranch_execz .LBB0_1142
	s_add_u32 s8, s78, 0x80200
	s_addc_u32 s9, s79, 0
	s_mov_b32 s24, 1
	s_branch .LBB0_1135

.LBB0_1139:
	global_load_dword v1, v0, s[6:7] sc1
	s_add_i32 s24, s24, 1
	s_mov_b64 s[18:19], -1
	s_waitcnt vmcnt(0)
	v_cmp_ge_u32_e32 vcc, v1, v5
	s_orn2_b64 s[22:23], vcc, exec
	s_branch .LBB0_1134

.LBB0_1244:
	s_or_b64 exec, exec, s[6:7]
	v_cvt_f32_u32_e32 v4, v2
	s_waitcnt vmcnt(0)
	v_readfirstlane_b32 s4, v3
	v_sub_u32_e32 v3, 0, v2
	v_rcp_iflag_f32_e32 v4, v4
	v_add_u32_e32 v5, s4, v1
	v_mul_f32_e32 v4, 0x4f7ffffe, v4
	v_cvt_u32_f32_e32 v4, v4
	v_mul_lo_u32 v1, v3, v4
	v_mul_hi_u32 v1, v4, v1
	v_add_u32_e32 v1, v4, v1
	v_mul_hi_u32 v1, v5, v1
	v_mul_lo_u32 v3, v1, v2
	v_sub_u32_e32 v3, v5, v3
	v_add_u32_e32 v4, 1, v1
	v_cmp_ge_u32_e32 vcc, v3, v2
	s_nop 1
	v_cndmask_b32_e32 v1, v1, v4, vcc
	v_sub_u32_e32 v4, v3, v2
	v_cndmask_b32_e32 v3, v3, v4, vcc
	v_add_u32_e32 v4, 1, v1
	v_cmp_ge_u32_e32 vcc, v3, v2
	v_add_u32_e32 v3, 1, v5
	s_nop 0
	v_cndmask_b32_e32 v1, v1, v4, vcc
	v_mul_lo_u32 v4, v2, v1
	v_add_u32_e32 v2, v4, v2
	v_cmp_ne_u32_e32 vcc, v3, v2
	s_and_saveexec_b64 s[4:5], vcc
	s_xor_b64 s[4:5], exec, s[4:5]
	s_cbranch_execz .LBB0_1258
	s_waitcnt lgkmcnt(0)
	v_readlane_b32 s98, v254, 38
	s_nop 3
	s_lshl_b32 s98, s98, 8
	s_sub_u32 s98, s2, s98
	s_subb_u32 s99, s3, 0
	s_add_u32 s10, s98, 0x3400
	s_addc_u32 s11, s99, 0
	v_mad_u32_u24 v1, v1, v0, v0
	v_mov_b32_e32 v0, 0
	global_load_dword v0, v0, s[10:11] sc1
	s_waitcnt vmcnt(0)
	v_cmp_lt_u32_e32 vcc, v0, v1
	s_and_saveexec_b64 s[6:7], vcc
	s_cbranch_execz .LBB0_1257
	s_add_u32 s8, s78, 0x80200
	s_addc_u32 s9, s79, 0
	s_mov_b32 s26, 1
	s_mov_b64 s[16:17], 0
	v_mov_b32_e32 v0, 0
	s_branch .LBB0_1248

.LBB0_1252:
	global_load_dword v2, v0, s[10:11] sc1
	s_add_i32 s26, s26, 1
	s_mov_b64 s[22:23], -1
	s_waitcnt vmcnt(0)
	v_cmp_ge_u32_e32 vcc, v2, v1
	s_orn2_b64 s[20:21], vcc, exec
	s_branch .LBB0_1247

.LBB0_1261:
	s_or_b64 exec, exec, s[6:7]
	v_cvt_f32_u32_e32 v3, v0
	s_waitcnt vmcnt(0)
	v_readfirstlane_b32 s4, v2
	s_add_u32 s6, s78, 0x83400
	s_addc_u32 s7, s79, 0
	v_rcp_iflag_f32_e32 v3, v3
	v_add_u32_e32 v1, s4, v1
	v_add_u32_e32 v4, 1, v1
	s_mov_b64 s[8:9], 0
	v_mul_f32_e32 v2, 0x4f7ffffe, v3
	v_cvt_u32_f32_e32 v2, v2
	v_sub_u32_e32 v3, 0, v0
	v_mul_lo_u32 v3, v3, v2
	v_mul_hi_u32 v3, v2, v3
	v_add_u32_e32 v2, v2, v3
	v_mul_hi_u32 v2, v1, v2
	v_mul_lo_u32 v3, v2, v0
	v_sub_u32_e32 v1, v1, v3
	v_add_u32_e32 v5, 1, v2
	v_cmp_ge_u32_e32 vcc, v1, v0
	v_sub_u32_e32 v3, v1, v0
	s_nop 0
	v_cndmask_b32_e32 v2, v2, v5, vcc
	v_cndmask_b32_e32 v1, v1, v3, vcc
	v_add_u32_e32 v3, 1, v2
	v_cmp_ge_u32_e32 vcc, v1, v0
	s_nop 1
	v_cndmask_b32_e32 v2, v2, v3, vcc
	v_mul_lo_u32 v1, v0, v2
	v_add_u32_e32 v0, v1, v0
	v_mov_b32_e32 v5, v0
	v_cmp_ne_u32_e32 vcc, v4, v0
	v_mov_b64_e32 v[0:1], s[6:7]
	s_and_saveexec_b64 s[4:5], vcc
	s_cbranch_execz .LBB0_1273
	v_mov_b32_e32 v0, 0
	global_load_dword v1, v0, s[6:7] sc1
	s_mov_b64 s[16:17], 0
	s_waitcnt vmcnt(0)
	v_cmp_lt_u32_e32 vcc, v1, v5
	s_and_saveexec_b64 s[10:11], vcc
	s_cbranch_execz .LBB0_1272
	s_add_u32 s8, s78, 0x80200
	s_addc_u32 s9, s79, 0
	s_mov_b32 s26, 1
	s_branch .LBB0_1265

.LBB0_1269:
	global_load_dword v1, v0, s[6:7] sc1
	s_add_i32 s26, s26, 1
	s_mov_b64 s[20:21], -1
	s_waitcnt vmcnt(0)
	v_cmp_ge_u32_e32 vcc, v1, v5
	s_orn2_b64 s[24:25], vcc, exec
	s_branch .LBB0_1264
